# v32 plus the small per-XCD-slot start stagger also on phase 10 (down-projection GEMM)
# speedup vs baseline: 1.0169x; 1.0169x over previous
; #define SEAM(k) do { if (IN(k) && IN((k) + 1)) xcd_barrier(xbar); } while (0)
; __global__ void __launch_bounds__(512, 2) fwd_mega(Params p) {
;     ...
;     SEAM(9);
;     if (IN(10)) {
;         pg8::Gemm g{P + G_RV, DFF, (const bf16_t*)(ws + WS_WDN), MP, DM, DFF}; pg8::StaticOrder S; S.init(MP, DM, G, cb);
.LBB0_1359:
	s_cmp_lt_i32 s66, 11
	s_cselect_b64 s[2:3], -1, 0
	s_and_b64 s[10:11], s[2:3], s[0:1]
	s_andn2_b64 vcc, exec, s[10:11]
	s_cbranch_vccnz .LBB0_1498
	s_and_b32 s98, s64, 7
	s_cmp_eq_u32 s98, 0
	s_cbranch_scc1 .Lstg10_done

;     DI bool next(int i, Unit& u) const {
;         const long L = (long)i * G + c; if (L >= nwg) return false;
;         int wgid = (int)L; { const int q = nwg / NXCD, r = nwg % NXCD, xcd = wgid % NXCD, off = wgid / NXCD; wgid = (xcd < r ? xcd * (q + 1) : r * (q + 1) + (xcd - r) * q) + off; }
; __global__ void __launch_bounds__(512, 2) fwd_mega(Params p) {
;     ...
;         pg8::Gemm g{P + G_RV, DFF, (const bf16_t*)(ws + WS_WDN), MP, DM, DFF}; pg8::StaticOrder S; S.init(MP, DM, G, cb);
;         EpiResid<false, false> E{p.xp, p.xs, p.out, P, (float*)(ws + WS_SSQ4)};
;         if (G == 256) { EpiDownFinal EF{p.out, p.g_final, (float*)(ws + WS_XBUF), (unsigned*)(ws + WS_XCNT), L + 131072}; pg8::gemm_phase<EpiDownFinal, true>(L, g, S, EF); }
;         else pg8::gemm_phase<EpiResid<false, false>, true>(L, g, S, E);
.Lstg10_done:
	s_add_u32 s38, s94, 0x13400000
	s_addc_u32 s39, s95, 0
	s_add_u32 s14, s94, 0x2980000
	s_addc_u32 s15, s95, 0
	s_add_u32 s12, s94, 0x186000
	s_addc_u32 s13, s95, 0
	s_cmpk_lg_i32 s65, 0x100
	s_cbranch_scc0 .LBB0_1364
	s_cmpk_lt_i32 s64, 0x400
	s_cselect_b64 s[2:3], -1, 0
	s_cmpk_gt_i32 s64, 0x3ff
	v_readfirstlane_b32 s4, v153
	s_cbranch_scc1 .LBB0_1365
	s_ashr_i32 s0, s64, 31
	s_lshr_b32 s0, s0, 29
	s_add_i32 s7, s64, s0
	s_and_b32 s0, s7, -8
	s_sub_i32 s5, s64, s0
	s_cmp_gt_i32 s5, -1
	s_cbranch_scc0 .LBB0_1366
	s_lshl_b32 s6, s5, 7
	s_ashr_i32 s0, s7, 3
	s_cbranch_execz .LBB0_1367
	s_branch .LBB0_1368
